# HGRN2 chunk loops (phase a and phase c): next unit's operand rows touched one unit ahead (throwaway loads) so the unit-top loads hit L2; stale waits dropped
# speedup vs baseline: 1.0102x; 1.0015x over previous
.LBB0_911:
	s_mov_b64 s[100:101], 0x1e00000
	s_mov_b64 s[10:11], s[58:59]
	s_load_dwordx2 s[14:15], s[10:11], 0x158
	s_mov_b64 s[10:11], s[58:59]
	s_mov_b64 s[12:13], s[58:59]
	s_load_dwordx2 s[10:11], s[10:11], 0x158
	s_and_b32 s19, s8, 0xfffff800
	s_and_b32 s20, s16, 0x7c0
	s_load_dwordx2 s[12:13], s[12:13], 0x158
	v_mbcnt_lo_u32_b32 v16, -1, 0
	v_mbcnt_hi_u32_b32 v16, -1, v16
	s_or_b32 s19, s19, s20
	v_add_u32_e32 v17, s61, v16
	s_bfe_u32 s20, s18, 0x20005
	v_lshlrev_b32_e32 v38, 3, v17
	s_lshl_b32 s21, s20, 8
	v_and_b32_e32 v18, 0x78, v38
	s_waitcnt lgkmcnt(0)
	s_add_u32 s14, s14, s21
	s_addc_u32 s15, s15, 0
	v_lshlrev_b32_e32 v156, 1, v18
	v_lshl_add_u64 v[0:1], s[14:15], 0, v[156:157]
	v_ashrrev_i32_e32 v21, 4, v17
	v_lshl_add_u64 v[0:1], v[0:1], 0, s[46:47]
	v_add_u32_e32 v2, s19, v21
	v_mad_i64_i32 v[2:3], s[14:15], v2, s83, v[0:1]
	v_add_co_u32_e32 v14, vcc, s72, v2
	v_add_u32_e32 v2, 0x200, v17
	s_nop 0
	v_addc_co_u32_e32 v15, vcc, 0, v3, vcc
	global_load_dwordx4 v[10:13], v[14:15], off
	v_ashrrev_i32_e32 v39, 4, v2
	s_lshl_b32 s14, s20, 9
	v_add_u32_e32 v2, s19, v39
	v_lshlrev_b32_e32 v3, 2, v18
	s_add_i32 s14, s14, 0
	v_add_u32_e32 v40, s43, v3
	v_add_u32_e32 v3, s14, v3
	v_mad_i64_i32 v[8:9], s[14:15], v2, s83, v[0:1]
	v_add_u32_e32 v34, 0x22400, v3
	v_add_co_u32_e32 v8, vcc, s72, v8
	ds_read_b128 v[4:7], v34
	ds_read_b128 v[0:3], v34 offset:16
	v_addc_co_u32_e32 v9, vcc, 0, v9, vcc
	global_load_dwordx4 v[22:25], v[14:15], off offset:1024
	global_load_dwordx4 v[26:29], v[8:9], off
	v_lshl_add_u64 v[74:75], v[14:15], 0, s[100:101]
	v_lshl_add_u64 v[76:77], v[8:9], 0, s[100:101]
	s_waitcnt lgkmcnt(0)
	v_sub_f32_e32 v20, 1.0, v6
	v_sub_f32_e32 v31, 1.0, v0
	v_sub_f32_e32 v32, 1.0, v1
	v_sub_f32_e32 v14, 1.0, v4
	v_sub_f32_e32 v15, 1.0, v5
	v_sub_f32_e32 v30, 1.0, v7
	v_sub_f32_e32 v33, 1.0, v2
	s_add_i32 s14, 0, 0x1fc00
	s_waitcnt vmcnt(0)
	v_lshlrev_b32_e32 v19, 16, v10
	v_lshlrev_b32_e32 v35, 16, v11
	v_lshlrev_b32_e32 v36, 16, v12
	v_and_b32_e32 v12, 0xffff0000, v12
	v_lshlrev_b32_e32 v37, 16, v13
	v_mul_f32_e32 v19, 0xbfb8aa3b, v19
	v_mul_f32_e32 v35, 0xbfb8aa3b, v35
	v_mul_f32_e32 v36, 0xbfb8aa3b, v36
	v_mul_f32_e32 v12, 0xbfb8aa3b, v12
	v_mul_f32_e32 v37, 0xbfb8aa3b, v37
	v_exp_f32_e32 v19, v19
	v_exp_f32_e32 v35, v35
	v_exp_f32_e32 v36, v36
	v_exp_f32_e32 v12, v12
	v_exp_f32_e32 v37, v37
	v_and_b32_e32 v10, 0xffff0000, v10
	v_and_b32_e32 v11, 0xffff0000, v11
	v_and_b32_e32 v13, 0xffff0000, v13
	v_mul_f32_e32 v10, 0xbfb8aa3b, v10
	v_mul_f32_e32 v11, 0xbfb8aa3b, v11
	v_mul_f32_e32 v13, 0xbfb8aa3b, v13
	v_exp_f32_e32 v10, v10
	v_exp_f32_e32 v11, v11
	v_exp_f32_e32 v41, v13
	v_add_f32_e32 v13, 1.0, v19
	v_add_f32_e32 v19, 1.0, v35
	v_add_f32_e32 v35, 1.0, v36
	v_add_f32_e32 v12, 1.0, v12
	v_add_f32_e32 v36, 1.0, v37
	v_rcp_f32_e32 v37, v19
	v_rcp_f32_e32 v35, v35
	v_rcp_f32_e32 v12, v12
	v_rcp_f32_e32 v13, v13
	v_add_f32_e32 v10, 1.0, v10
	v_add_f32_e32 v11, 1.0, v11
	v_rcp_f32_e32 v10, v10
	v_rcp_f32_e32 v11, v11
	v_rcp_f32_e32 v36, v36
	v_fma_f32 v6, v20, v37, v6
	v_fma_f32 v20, v35, v31, v0
	v_fma_f32 v0, v12, v32, v1
	v_add_f32_e32 v1, 1.0, v41
	v_fma_f32 v19, v14, v13, v4
	v_rcp_f32_e32 v4, v1
	v_fma_f32 v5, v15, v10, v5
	v_fmac_f32_e32 v7, v30, v11
	v_fma_f32 v1, v36, v33, v2
	v_sub_f32_e32 v2, 1.0, v3
	v_log_f32_e32 v10, v19
	v_log_f32_e32 v11, v5
	v_log_f32_e32 v12, v6
	v_log_f32_e32 v13, v7
	v_fmac_f32_e32 v3, v4, v2
	v_log_f32_e32 v14, v20
	v_log_f32_e32 v30, v1
	v_log_f32_e32 v31, v3
	v_log_f32_e32 v15, v0
	v_lshlrev_b32_e32 v2, 9, v21
	v_pk_mul_f32 v[12:13], v[12:13], s[70:71] op_sel_hi:[1,0]
	v_pk_mul_f32 v[10:11], v[10:11], s[70:71] op_sel_hi:[1,0]
	v_add_u32_e32 v4, v40, v2
	v_pk_mul_f32 v[32:33], v[30:31], s[70:71] op_sel_hi:[1,0]
	v_pk_mul_f32 v[30:31], v[14:15], s[70:71] op_sel_hi:[1,0]
	ds_write_b128 v4, v[10:13]
	ds_write_b128 v4, v[30:33] offset:16
	v_bitop3_b32 v2, v21, 56, v38 bitop3:0x48
	v_lshlrev_b32_e32 v10, 1, v21
	v_lshlrev_b32_e32 v2, 1, v2
	v_and_b32_e32 v10, 14, v10
	v_add3_u32 v2, 0, v2, v10
	v_mad_u32_u24 v10, v18, s85, v2
	ds_write_b16 v10, v22 offset:44032
	ds_write_b16_d16_hi v10, v22 offset:44176
	ds_write_b16 v10, v23 offset:44320
	ds_write_b16_d16_hi v10, v23 offset:44464
	ds_write_b16 v10, v24 offset:44608
	ds_write_b16_d16_hi v10, v24 offset:44752
	ds_write_b16 v10, v25 offset:44896
	ds_write_b16_d16_hi v10, v25 offset:45040
	global_load_dwordx4 v[30:33], v[8:9], off offset:1024
	v_lshlrev_b32_e32 v8, 16, v26
	v_mul_f32_e32 v8, 0xbfb8aa3b, v8
	v_exp_f32_e32 v24, v8
	v_and_b32_e32 v21, 0xffff0000, v26
	ds_read_b128 v[12:15], v34
	ds_read_b128 v[8:11], v34 offset:16
	v_mul_f32_e32 v21, 0xbfb8aa3b, v21
	v_add_f32_e32 v24, 1.0, v24
	v_rcp_f32_e32 v24, v24
	v_exp_f32_e32 v25, v21
	v_lshlrev_b32_e32 v22, 16, v27
	s_waitcnt lgkmcnt(1)
	v_sub_f32_e32 v21, 1.0, v12
	v_fma_f32 v21, v24, v21, v12
	v_add_f32_e32 v12, 1.0, v25
	v_mul_f32_e32 v22, 0xbfb8aa3b, v22
	v_rcp_f32_e32 v12, v12
	v_exp_f32_e32 v26, v22
	v_and_b32_e32 v23, 0xffff0000, v27
	v_sub_f32_e32 v22, 1.0, v13
	v_fma_f32 v22, v12, v22, v13
	v_add_f32_e32 v12, 1.0, v26
	v_mul_f32_e32 v13, 0xbfb8aa3b, v23
	v_rcp_f32_e32 v12, v12
	v_exp_f32_e32 v13, v13
	v_lshlrev_b32_e32 v27, 16, v28
	v_sub_f32_e32 v23, 1.0, v14
	v_fma_f32 v12, v12, v23, v14
	v_add_f32_e32 v13, 1.0, v13
	v_mul_f32_e32 v14, 0xbfb8aa3b, v27
	v_rcp_f32_e32 v13, v13
	v_exp_f32_e32 v14, v14
	v_and_b32_e32 v28, 0xffff0000, v28
	v_sub_f32_e32 v23, 1.0, v15
	v_fmac_f32_e32 v15, v13, v23
	v_add_f32_e32 v13, 1.0, v14
	v_mul_f32_e32 v14, 0xbfb8aa3b, v28
	v_rcp_f32_e32 v13, v13
	v_exp_f32_e32 v14, v14
	s_waitcnt lgkmcnt(0)
	v_sub_f32_e32 v23, 1.0, v8
	v_lshlrev_b32_e32 v35, 16, v29
	v_fma_f32 v8, v13, v23, v8
	v_add_f32_e32 v13, 1.0, v14
	v_rcp_f32_e32 v13, v13
	v_and_b32_e32 v29, 0xffff0000, v29
	v_sub_f32_e32 v14, 1.0, v9
	v_mul_f32_e32 v23, 0xbfb8aa3b, v35
	v_exp_f32_e32 v23, v23
	v_fma_f32 v9, v13, v14, v9
	v_mul_f32_e32 v13, 0xbfb8aa3b, v29
	v_exp_f32_e32 v13, v13
	v_add_f32_e32 v14, 1.0, v23
	v_rcp_f32_e32 v14, v14
	v_sub_f32_e32 v23, 1.0, v10
	v_add_f32_e32 v13, 1.0, v13
	v_rcp_f32_e32 v13, v13
	v_fma_f32 v10, v14, v23, v10
	v_sub_f32_e32 v14, 1.0, v11
	v_log_f32_e32 v24, v21
	v_log_f32_e32 v25, v22
	v_log_f32_e32 v26, v12
	v_log_f32_e32 v27, v15
	v_fmac_f32_e32 v11, v13, v14
	v_lshlrev_b32_e32 v13, 9, v39
	v_log_f32_e32 v28, v8
	v_log_f32_e32 v34, v10
	v_log_f32_e32 v35, v11
	v_log_f32_e32 v29, v9
	v_add_u32_e32 v14, v40, v13
	v_bitop3_b32 v13, v39, 56, v38 bitop3:0x48
	v_lshlrev_b32_e32 v23, 1, v39
	v_lshlrev_b32_e32 v13, 1, v13
	v_and_b32_e32 v23, 14, v23
	v_add3_u32 v13, 0, v13, v23
	v_pk_mul_f32 v[26:27], v[26:27], s[70:71] op_sel_hi:[1,0]
	v_pk_mul_f32 v[24:25], v[24:25], s[70:71] op_sel_hi:[1,0]
	v_mad_u32_u24 v23, v18, s85, v13
	v_pk_mul_f32 v[36:37], v[34:35], s[70:71] op_sel_hi:[1,0]
	v_pk_mul_f32 v[34:35], v[28:29], s[70:71] op_sel_hi:[1,0]
	ds_write_b128 v14, v[24:27]
	ds_write_b128 v14, v[34:37] offset:16
	s_waitcnt vmcnt(0)
	s_add_i32 s100, s18, s50
	s_cmpk_gt_i32 s100, 0x3ff
	s_cbranch_scc1 .La64pf_skip
	global_load_dwordx4 v[70:73], v[74:75], off
	global_load_dwordx4 v[70:73], v[74:75], off offset:1024
	global_load_dwordx4 v[70:73], v[76:77], off
	global_load_dwordx4 v[70:73], v[76:77], off offset:1024
.La64pf_skip:
	ds_write_b16 v23, v30 offset:44032
	ds_write_b16_d16_hi v23, v30 offset:44176
	ds_write_b16 v23, v31 offset:44320
	ds_write_b16_d16_hi v23, v31 offset:44464
	ds_write_b16 v23, v32 offset:44608
	ds_write_b16_d16_hi v23, v32 offset:44752
	ds_write_b16 v23, v33 offset:44896
	ds_write_b16_d16_hi v23, v33 offset:45040
	v_and_b32_e32 v23, 0x7f, v17
	v_ashrrev_i32_e32 v41, 7, v17
	v_lshlrev_b32_e32 v24, 13, v41
	v_lshlrev_b32_e32 v48, 2, v23
	v_add3_u32 v23, s43, v24, v48
	s_waitcnt lgkmcnt(0)
	s_barrier
	ds_read2st64_b32 v[26:27], v23 offset1:2
	ds_read2st64_b32 v[28:29], v23 offset0:4 offset1:6
	ds_read2st64_b32 v[30:31], v23 offset0:8 offset1:10
	ds_read2st64_b32 v[34:35], v23 offset0:12 offset1:14
	ds_read2st64_b32 v[36:37], v23 offset0:16 offset1:18
	s_waitcnt lgkmcnt(4)
	v_add_f32_e32 v25, 0, v26
	v_add_f32_e32 v27, v25, v27
	s_waitcnt lgkmcnt(3)
	v_add_f32_e32 v26, v27, v28
	v_add_f32_e32 v29, v26, v29
	s_waitcnt lgkmcnt(2)
	v_add_f32_e32 v28, v29, v30
	v_add_f32_e32 v32, v28, v31
	ds_read2st64_b32 v[42:43], v23 offset0:20 offset1:22
	s_waitcnt lgkmcnt(2)
	v_add_f32_e32 v30, v32, v34
	v_add_f32_e32 v31, v30, v35
	ds_read2st64_b32 v[44:45], v23 offset0:24 offset1:26
	s_waitcnt lgkmcnt(2)
	v_add_f32_e32 v33, v31, v36
	v_add_f32_e32 v34, v33, v37
	ds_read2st64_b32 v[46:47], v23 offset0:28 offset1:30
	s_waitcnt lgkmcnt(2)
	v_add_f32_e32 v39, v34, v42
	v_add_f32_e32 v40, v39, v43
	s_waitcnt lgkmcnt(1)
	v_add_f32_e32 v37, v40, v44
	v_add_f32_e32 v38, v37, v45
	s_waitcnt lgkmcnt(0)
	v_add_f32_e32 v35, v38, v46
	v_add_f32_e32 v36, v35, v47
	v_lshl_add_u32 v42, v17, 2, s14
	v_mov_b32_e32 v24, 0
	ds_write_b32 v42, v36
	v_add_u32_e32 v42, s14, v48
	v_cmp_lt_i32_e32 vcc, 0, v41
	s_waitcnt lgkmcnt(0)
	s_barrier
	s_and_saveexec_b64 s[14:15], vcc
	s_cbranch_execz .LBB0_917
	ds_read_b32 v24, v42
	s_waitcnt lgkmcnt(0)
	v_add_f32_e32 v24, 0, v24
	s_or_b64 exec, exec, s[14:15]
	v_cmp_lt_i32_e32 vcc, 1, v41
	s_and_saveexec_b64 s[14:15], vcc
	s_cbranch_execnz .LBB0_918

.LBB0_1032:
	s_mov_b64 s[100:101], 0x1e00000
	s_mov_b64 s[0:1], s[58:59]
	s_load_dwordx2 s[10:11], s[0:1], 0x158
	s_mov_b64 s[0:1], s[58:59]
	s_mov_b64 s[12:13], s[58:59]
	s_load_dwordx2 s[16:17], s[0:1], 0x158
	s_waitcnt lgkmcnt(0)
	s_add_u32 s1, s10, 0x12f00000
	s_addc_u32 s22, s11, 0
	s_load_dwordx2 s[10:11], s[12:13], 0x90
	s_mov_b64 s[12:13], s[58:59]
	s_and_b32 s0, s8, 0xfffff800
	s_and_b32 s14, s20, 0x7c0
	s_load_dwordx2 s[12:13], s[12:13], 0x158
	v_mbcnt_lo_u32_b32 v25, -1, 0
	v_mbcnt_hi_u32_b32 v25, -1, v25
	s_or_b32 s14, s0, s14
	v_add_u32_e32 v40, s61, v25
	s_bfe_u32 s0, s56, 0x20005
	v_lshlrev_b32_e32 v11, 3, v40
	s_lshl_b32 s15, s0, 8
	v_and_b32_e32 v9, 0x78, v11
	s_add_u32 s18, s1, s15
	s_addc_u32 s19, s22, 0
	v_lshlrev_b32_e32 v156, 1, v9
	v_ashrrev_i32_e32 v24, 4, v40
	v_lshl_add_u64 v[0:1], s[18:19], 0, v[156:157]
	v_add_u32_e32 v2, s14, v24
	v_mad_i64_i32 v[4:5], s[18:19], v2, s83, v[0:1]
	v_add_co_u32_e32 v6, vcc, s72, v4
	v_add_u32_e32 v27, 0x200, v40
	s_nop 0
	v_addc_co_u32_e32 v7, vcc, 0, v5, vcc
	global_load_dwordx4 v[12:15], v[6:7], off
	v_ashrrev_i32_e32 v26, 4, v27
	s_lshl_b32 s15, s0, 9
	v_lshlrev_b32_e32 v2, 2, v9
	v_add_u32_e32 v3, s14, v26
	s_add_i32 s15, s15, 0
	v_add_u32_e32 v10, s43, v2
	v_mad_i64_i32 v[0:1], s[18:19], v3, s83, v[0:1]
	v_add_u32_e32 v2, s15, v2
	v_add_u32_e32 v50, 0x22400, v2
	v_add_co_u32_e32 v42, vcc, s72, v0
	ds_read_b128 v[16:19], v50
	s_nop 0
	v_addc_co_u32_e32 v43, vcc, 0, v1, vcc
	v_lshl_add_u64 v[110:111], v[0:1], 0, s[100:101]
	global_load_dwordx4 v[0:3], v[0:1], off offset:3072
	s_nop 0
	global_load_dwordx4 v[20:23], v[6:7], off offset:1024
	global_load_dwordx4 v[70:73], v[6:7], off offset:2048
	global_load_dwordx4 v[74:77], v[42:43], off offset:2048
	global_load_dwordx4 v[102:105], v[42:43], off offset:1024
	v_lshlrev_b32_e32 v78, 9, v24
	v_lshlrev_b32_e32 v79, 4, v40
	v_and_b32_e32 v79, 0xf0, v79
	v_or_b32_e32 v78, v78, v79
	v_mov_b32_e32 v79, 0
	v_lshl_add_u64 v[78:79], s[16:17], 0, v[78:79]
	v_lshl_add_u64 v[78:79], v[78:79], 0, s[4:5]
	v_mov_b32_e32 v80, 0x4000
	v_mov_b32_e32 v81, 0
	v_lshl_add_u64 v[80:81], v[78:79], 0, v[80:81]
	global_load_dwordx4 v[82:85], v[78:79], off
	global_load_dwordx4 v[86:89], v[78:79], off offset:256
	global_load_dwordx4 v[94:97], v[80:81], off
	global_load_dwordx4 v[98:101], v[80:81], off offset:256
	s_nop 0
	v_lshl_add_u64 v[112:113], v[4:5], 0, s[100:101]
	v_lshl_add_u64 v[106:107], v[6:7], 0, s[100:101]
	v_lshl_add_u64 v[108:109], v[42:43], 0, s[100:101]
	v_lshl_add_u64 v[114:115], v[78:79], 0, s[6:7]
	v_lshl_add_u64 v[116:117], v[80:81], 0, s[6:7]
	global_load_dwordx4 v[4:7], v[4:5], off offset:3072
	ds_read_b128 v[28:31], v50 offset:16
	global_load_dwordx4 v[32:35], v[42:43], off
	s_waitcnt lgkmcnt(0)
	v_mov_b32_e32 v37, v18
	v_mov_b32_e32 v18, v17
	v_mov_b32_e32 v36, v16
	v_mov_b32_e32 v16, v28
	v_pk_add_f32 v[44:45], v[18:19], 1.0 op_sel_hi:[1,0] neg_lo:[1,0] neg_hi:[1,0]
	v_pk_add_f32 v[38:39], v[36:37], 1.0 op_sel_hi:[1,0] neg_lo:[1,0] neg_hi:[1,0]
	v_mul_u32_u24_e32 v52, 0x90, v9
	s_waitcnt vmcnt(0)
	s_add_i32 s100, s56, s62
	s_cmpk_gt_i32 s100, 0x3ff
	s_cbranch_scc1 .Lc64pf_skip
	global_load_dwordx4 v[120:123], v[106:107], off
	global_load_dwordx4 v[120:123], v[106:107], off offset:1024
	global_load_dwordx4 v[120:123], v[106:107], off offset:2048
	global_load_dwordx4 v[120:123], v[108:109], off
	global_load_dwordx4 v[120:123], v[108:109], off offset:1024
	global_load_dwordx4 v[120:123], v[108:109], off offset:2048
	global_load_dwordx4 v[120:123], v[110:111], off offset:3072
	global_load_dwordx4 v[120:123], v[112:113], off offset:3072
	global_load_dwordx4 v[120:123], v[114:115], off
	global_load_dwordx4 v[120:123], v[114:115], off offset:256
	global_load_dwordx4 v[120:123], v[116:117], off
	global_load_dwordx4 v[120:123], v[116:117], off offset:256
.Lc64pf_skip:
	v_lshlrev_b32_e32 v8, 16, v12
	v_and_b32_e32 v12, 0xffff0000, v12
	v_lshlrev_b32_e32 v17, 16, v13
	v_and_b32_e32 v13, 0xffff0000, v13
	v_lshlrev_b32_e32 v28, 16, v14
	v_and_b32_e32 v14, 0xffff0000, v14
	v_lshlrev_b32_e32 v41, 16, v15
	v_and_b32_e32 v15, 0xffff0000, v15
	v_mul_f32_e32 v12, 0xbfb8aa3b, v12
	v_mul_f32_e32 v13, 0xbfb8aa3b, v13
	v_mul_f32_e32 v8, 0xbfb8aa3b, v8
	v_mul_f32_e32 v17, 0xbfb8aa3b, v17
	v_mul_f32_e32 v28, 0xbfb8aa3b, v28
	v_mul_f32_e32 v14, 0xbfb8aa3b, v14
	v_mul_f32_e32 v41, 0xbfb8aa3b, v41
	v_mul_f32_e32 v15, 0xbfb8aa3b, v15
	v_exp_f32_e32 v12, v12
	v_exp_f32_e32 v13, v13
	v_exp_f32_e32 v8, v8
	v_exp_f32_e32 v17, v17
	v_exp_f32_e32 v28, v28
	v_exp_f32_e32 v14, v14
	v_exp_f32_e32 v41, v41
	v_exp_f32_e32 v15, v15
	v_add_f32_e32 v46, 1.0, v12
	v_add_f32_e32 v47, 1.0, v13
	v_add_f32_e32 v8, 1.0, v8
	v_add_f32_e32 v17, 1.0, v17
	v_add_f32_e32 v28, 1.0, v28
	v_add_f32_e32 v48, 1.0, v14
	v_add_f32_e32 v41, 1.0, v41
	v_add_f32_e32 v49, 1.0, v15
	v_rcp_f32_e32 v14, v46
	v_rcp_f32_e32 v15, v47
	v_rcp_f32_e32 v12, v8
	v_rcp_f32_e32 v13, v17
	v_rcp_f32_e32 v46, v28
	v_rcp_f32_e32 v47, v41
	v_rcp_f32_e32 v48, v48
	v_rcp_f32_e32 v49, v49
	v_mov_b32_e32 v17, v30
	v_pk_fma_f32 v[14:15], v[14:15], v[44:45], v[18:19]
	v_pk_add_f32 v[18:19], v[16:17], 1.0 op_sel_hi:[1,0] neg_lo:[1,0] neg_hi:[1,0]
	v_mov_b32_e32 v30, v29
	v_pk_fma_f32 v[12:13], v[12:13], v[38:39], v[36:37]
	v_pk_fma_f32 v[16:17], v[46:47], v[18:19], v[16:17]
	v_pk_add_f32 v[18:19], v[30:31], 1.0 op_sel_hi:[1,0] neg_lo:[1,0] neg_hi:[1,0]
	v_log_f32_e32 v36, v12
	v_log_f32_e32 v37, v14
	v_log_f32_e32 v38, v13
	v_log_f32_e32 v39, v15
	v_pk_fma_f32 v[18:19], v[48:49], v[18:19], v[30:31]
	v_log_f32_e32 v44, v16
	v_log_f32_e32 v46, v17
	v_log_f32_e32 v47, v19
	v_log_f32_e32 v45, v18
	v_lshlrev_b32_e32 v8, 9, v24
	v_pk_mul_f32 v[30:31], v[38:39], s[70:71] op_sel_hi:[1,0]
	v_pk_mul_f32 v[28:29], v[36:37], s[70:71] op_sel_hi:[1,0]
	v_add_u32_e32 v41, v10, v8
	v_bitop3_b32 v8, v24, 56, v11 bitop3:0x48
	v_pk_mul_f32 v[38:39], v[46:47], s[70:71] op_sel_hi:[1,0]
	v_pk_mul_f32 v[36:37], v[44:45], s[70:71] op_sel_hi:[1,0]
	ds_write_b128 v41, v[28:31]
	ds_write_b128 v41, v[36:39] offset:16
	v_lshl_add_u32 v28, v8, 1, 0
	v_lshlrev_b32_e32 v8, 1, v24
	v_and_b32_e32 v29, 14, v8
	v_add3_u32 v28, v28, v29, v52
	ds_write_b16 v28, v20 offset:44032
	ds_write_b16_d16_hi v28, v20 offset:44176
	ds_write_b16 v28, v21 offset:44320
	ds_write_b16_d16_hi v28, v21 offset:44464
	ds_write_b16 v28, v22 offset:44608
	ds_write_b16_d16_hi v28, v22 offset:44752
	v_mov_b32_e32 v36, v102
	v_mov_b32_e32 v37, v103
	v_mov_b32_e32 v38, v104
	v_mov_b32_e32 v39, v105
	v_and_b32_e32 v21, 0xffff0000, v32
	v_lshlrev_b32_e32 v20, 16, v32
	v_lshlrev_b32_e32 v22, 16, v33
	v_mul_f32_e32 v21, 0xbfb8aa3b, v21
	ds_write_b16 v28, v23 offset:44896
	ds_write_b16_d16_hi v28, v23 offset:45040
	v_and_b32_e32 v23, 0xffff0000, v33
	v_mul_f32_e32 v20, 0xbfb8aa3b, v20
	v_exp_f32_e32 v21, v21
	v_mul_f32_e32 v22, 0xbfb8aa3b, v22
	v_exp_f32_e32 v20, v20
	v_exp_f32_e32 v32, v22
	v_mul_f32_e32 v22, 0xbfb8aa3b, v23
	v_exp_f32_e32 v23, v22
	ds_read_b128 v[28:31], v50
	ds_read_b128 v[42:45], v50 offset:16
	v_add_f32_e32 v21, 1.0, v21
	v_add_f32_e32 v20, 1.0, v20
	v_rcp_f32_e32 v22, v21
	v_add_f32_e32 v21, 1.0, v32
	v_rcp_f32_e32 v20, v20
	v_rcp_f32_e32 v21, v21
	v_add_f32_e32 v23, 1.0, v23
	v_rcp_f32_e32 v23, v23
	s_waitcnt lgkmcnt(1)
	v_mov_b32_e32 v32, v28
	v_mov_b32_e32 v33, v30
	v_lshlrev_b32_e32 v46, 16, v34
	v_and_b32_e32 v47, 0xffff0000, v34
	v_lshlrev_b32_e32 v48, 16, v35
	v_and_b32_e32 v49, 0xffff0000, v35
	v_pk_add_f32 v[34:35], v[32:33], 1.0 op_sel_hi:[1,0] neg_lo:[1,0] neg_hi:[1,0]
	v_mov_b32_e32 v30, v29
	v_pk_fma_f32 v[20:21], v[20:21], v[34:35], v[32:33]
	v_pk_add_f32 v[32:33], v[30:31], 1.0 op_sel_hi:[1,0] neg_lo:[1,0] neg_hi:[1,0]
	v_log_f32_e32 v28, v20
	v_pk_fma_f32 v[22:23], v[22:23], v[32:33], v[30:31]
	v_mul_f32_e32 v31, 0xbfb8aa3b, v47
	v_mul_f32_e32 v30, 0xbfb8aa3b, v46
	v_exp_f32_e32 v31, v31
	v_mul_f32_e32 v32, 0xbfb8aa3b, v48
	v_exp_f32_e32 v30, v30
	v_exp_f32_e32 v32, v32
	v_mul_f32_e32 v33, 0xbfb8aa3b, v49
	v_exp_f32_e32 v33, v33
	v_add_f32_e32 v31, 1.0, v31
	v_add_f32_e32 v30, 1.0, v30
	v_rcp_f32_e32 v46, v31
	v_add_f32_e32 v31, 1.0, v32
	v_rcp_f32_e32 v30, v30
	v_rcp_f32_e32 v31, v31
	v_add_f32_e32 v32, 1.0, v33
	v_rcp_f32_e32 v47, v32
	s_waitcnt lgkmcnt(0)
	v_mov_b32_e32 v32, v42
	v_mov_b32_e32 v33, v44
	v_pk_add_f32 v[48:49], v[32:33], 1.0 op_sel_hi:[1,0] neg_lo:[1,0] neg_hi:[1,0]
	v_mov_b32_e32 v44, v43
	v_pk_fma_f32 v[32:33], v[30:31], v[48:49], v[32:33]
	v_pk_add_f32 v[30:31], v[44:45], 1.0 op_sel_hi:[1,0] neg_lo:[1,0] neg_hi:[1,0]
	v_log_f32_e32 v29, v22
	v_pk_fma_f32 v[30:31], v[46:47], v[30:31], v[44:45]
	v_log_f32_e32 v42, v32
	v_log_f32_e32 v48, v33
	v_log_f32_e32 v49, v31
	v_log_f32_e32 v43, v30
	v_log_f32_e32 v34, v21
	v_log_f32_e32 v35, v23
	v_pk_mul_f32 v[44:45], v[28:29], s[70:71] op_sel_hi:[1,0]
	v_lshlrev_b32_e32 v28, 9, v26
	v_pk_mul_f32 v[50:51], v[48:49], s[70:71] op_sel_hi:[1,0]
	v_pk_mul_f32 v[48:49], v[42:43], s[70:71] op_sel_hi:[1,0]
	v_add_u32_e32 v42, v10, v28
	v_bitop3_b32 v10, v26, 56, v11 bitop3:0x48
	v_lshl_add_u32 v28, v10, 1, 0
	v_lshlrev_b32_e32 v10, 1, v26
	v_and_b32_e32 v29, 14, v10
	v_pk_mul_f32 v[46:47], v[34:35], s[70:71] op_sel_hi:[1,0]
	v_add3_u32 v28, v28, v29, v52
	ds_write_b128 v42, v[44:47]
	ds_write_b128 v42, v[48:51] offset:16
	ds_write_b16 v28, v36 offset:44032
	ds_write_b16_d16_hi v28, v36 offset:44176
	ds_write_b16 v28, v37 offset:44320
	ds_write_b16_d16_hi v28, v37 offset:44464
	ds_write_b16 v28, v38 offset:44608
	ds_write_b16_d16_hi v28, v38 offset:44752
	ds_write_b16 v28, v39 offset:44896
	ds_write_b16_d16_hi v28, v39 offset:45040
	v_and_b32_e32 v29, 0x7f, v40
	v_ashrrev_i32_e32 v28, 7, v40
	v_lshlrev_b32_e32 v34, 13, v28
	v_lshlrev_b32_e32 v29, 2, v29
	v_add3_u32 v43, s43, v34, v29
	s_waitcnt lgkmcnt(0)
	s_barrier
	ds_read2st64_b32 v[34:35], v43 offset1:2
	ds_read2st64_b32 v[36:37], v43 offset0:4 offset1:6
	ds_read2st64_b32 v[38:39], v43 offset0:8 offset1:10
	v_mov_b32_e32 v44, 0
	v_add_u32_e32 v29, 0, v29
	s_waitcnt lgkmcnt(2)
	v_add_f32_e32 v45, 0, v34
	v_add_f32_e32 v47, v45, v35
	ds_read2st64_b32 v[34:35], v43 offset0:12 offset1:14
	s_waitcnt lgkmcnt(2)
	v_add_f32_e32 v46, v47, v36
	v_add_f32_e32 v49, v46, v37
	s_waitcnt lgkmcnt(1)
	v_add_f32_e32 v48, v49, v38
	ds_read2st64_b32 v[36:37], v43 offset0:16 offset1:18
	v_add_f32_e32 v52, v48, v39
	s_waitcnt lgkmcnt(1)
	v_add_f32_e32 v50, v52, v34
	v_add_f32_e32 v51, v50, v35
	ds_read2st64_b32 v[34:35], v43 offset0:20 offset1:22
	ds_read2st64_b32 v[38:39], v43 offset0:24 offset1:26
	s_waitcnt lgkmcnt(2)
	v_add_f32_e32 v53, v51, v36
	v_add_f32_e32 v54, v53, v37
	ds_read2st64_b32 v[36:37], v43 offset0:28 offset1:30
	s_waitcnt lgkmcnt(2)
	v_add_f32_e32 v59, v54, v34
	v_add_f32_e32 v60, v59, v35
	s_waitcnt lgkmcnt(1)
	v_add_f32_e32 v57, v60, v38
	v_add_f32_e32 v58, v57, v39
	s_waitcnt lgkmcnt(0)
	v_add_f32_e32 v55, v58, v36
	v_add_f32_e32 v56, v55, v37
	v_lshl_add_u32 v34, v40, 2, 0
	v_cmp_lt_i32_e32 vcc, 0, v28
	ds_write_b32 v34, v56 offset:62464
	s_waitcnt lgkmcnt(0)
	s_barrier
	s_and_saveexec_b64 s[18:19], vcc
	s_cbranch_execz .LBB0_1040
	ds_read_b32 v34, v29 offset:62464
	s_waitcnt lgkmcnt(0)
	v_add_f32_e32 v44, 0, v34
	s_or_b64 exec, exec, s[18:19]
	v_cmp_lt_i32_e32 vcc, 1, v28
	s_and_saveexec_b64 s[18:19], vcc
	s_cbranch_execnz .LBB0_1041

.LBB0_1038:
	s_or_b64 exec, exec, s[18:19]
	v_lshlrev_b32_e32 v4, 16, v4
	v_mul_f32_e32 v43, 0xbfb8aa3b, v4
	v_exp_f32_e32 v43, v43
	v_mul_f32_e32 v44, 0xbfb8aa3b, v38
	v_exp_f32_e32 v45, v44
	v_lshlrev_b32_e32 v5, 16, v5
	v_add_f32_e32 v43, 1.0, v43
	v_rcp_f32_e32 v44, v43
	v_add_f32_e32 v43, 1.0, v45
	v_mul_f32_e32 v45, 0xbfb8aa3b, v5
	v_exp_f32_e32 v45, v45
	v_mul_f32_e32 v46, 0xbfb8aa3b, v39
	v_exp_f32_e32 v47, v46
	v_rcp_f32_e32 v46, v43
	v_add_f32_e32 v43, 1.0, v45
	v_rcp_f32_e32 v45, v43
	v_add_f32_e32 v43, 1.0, v47
	v_lshlrev_b32_e32 v6, 16, v6
	v_rcp_f32_e32 v47, v43
	v_mul_f32_e32 v43, 0xbfb8aa3b, v6
	v_exp_f32_e32 v43, v43
	v_mul_f32_e32 v48, 0xbfb8aa3b, v36
	v_exp_f32_e32 v49, v48
	v_lshlrev_b32_e32 v7, 16, v7
	v_add_f32_e32 v43, 1.0, v43
	v_rcp_f32_e32 v48, v43
	v_add_f32_e32 v43, 1.0, v49
	v_mul_f32_e32 v49, 0xbfb8aa3b, v7
	v_exp_f32_e32 v49, v49
	v_mul_f32_e32 v50, 0xbfb8aa3b, v37
	v_exp_f32_e32 v51, v50
	v_rcp_f32_e32 v50, v43
	v_add_f32_e32 v43, 1.0, v49
	v_rcp_f32_e32 v49, v43
	v_add_f32_e32 v43, 1.0, v51
	v_lshlrev_b32_e32 v0, 16, v0
	v_rcp_f32_e32 v51, v43
	v_mul_f32_e32 v43, 0xbfb8aa3b, v0
	v_exp_f32_e32 v43, v43
	v_mul_f32_e32 v52, 0xbfb8aa3b, v34
	v_exp_f32_e32 v53, v52
	v_lshlrev_b32_e32 v1, 16, v1
	v_add_f32_e32 v43, 1.0, v43
	v_rcp_f32_e32 v52, v43
	v_add_f32_e32 v43, 1.0, v53
	v_mul_f32_e32 v53, 0xbfb8aa3b, v1
	v_exp_f32_e32 v53, v53
	v_mul_f32_e32 v54, 0xbfb8aa3b, v35
	v_exp_f32_e32 v55, v54
	v_rcp_f32_e32 v54, v43
	v_add_f32_e32 v43, 1.0, v53
	v_lshlrev_b32_e32 v56, 16, v2
	v_rcp_f32_e32 v53, v43
	v_add_f32_e32 v43, 1.0, v55
	v_mul_f32_e32 v2, 0xbfb8aa3b, v56
	v_rcp_f32_e32 v55, v43
	v_exp_f32_e32 v2, v2
	v_mul_f32_e32 v43, 0xbfb8aa3b, v28
	v_exp_f32_e32 v43, v43
	v_lshlrev_b32_e32 v57, 16, v3
	v_add_f32_e32 v2, 1.0, v2
	v_mul_f32_e32 v3, 0xbfb8aa3b, v57
	v_rcp_f32_e32 v58, v2
	v_add_f32_e32 v2, 1.0, v43
	v_exp_f32_e32 v3, v3
	v_mul_f32_e32 v43, 0xbfb8aa3b, v29
	v_exp_f32_e32 v43, v43
	v_rcp_f32_e32 v60, v2
	v_add_f32_e32 v2, 1.0, v3
	v_pk_mul_f32 v[36:37], v[50:51], v[36:37]
	v_pk_mul_f32 v[50:51], v[52:53], v[0:1]
	v_lshl_add_u32 v0, v9, 2, 0
	v_rcp_f32_e32 v59, v2
	v_add_f32_e32 v2, 1.0, v43
	v_add_u32_e32 v9, 0x1bc00, v0
	v_rcp_f32_e32 v61, v2
	v_pk_mul_f32 v[44:45], v[44:45], v[4:5]
	v_pk_mul_f32 v[48:49], v[48:49], v[6:7]
	ds_read_b128 v[0:3], v9
	ds_read_b128 v[4:7], v41
	v_pk_add_f32 v[62:63], v[12:13], 1.0 op_sel_hi:[1,0] neg_lo:[1,0] neg_hi:[1,0]
	v_pk_add_f32 v[64:65], v[14:15], 1.0 op_sel_hi:[1,0] neg_lo:[1,0] neg_hi:[1,0]
	v_pk_mul_f32 v[38:39], v[46:47], v[38:39]
	v_pk_add_f32 v[46:47], v[16:17], 1.0 op_sel_hi:[1,0] neg_lo:[1,0] neg_hi:[1,0]
	v_pk_add_f32 v[66:67], v[18:19], 1.0 op_sel_hi:[1,0] neg_lo:[1,0] neg_hi:[1,0]
	ds_read_b128 v[12:15], v9 offset:16
	ds_read_b128 v[16:19], v41 offset:16
	s_waitcnt lgkmcnt(2)
	v_sub_f32_e32 v1, v5, v1
	v_mul_f32_e32 v5, 0x3fb8aa3b, v1
	v_mul_f32_e32 v1, 0xbfb8aa3b, v1
	v_sub_f32_e32 v2, v6, v2
	v_pk_mul_f32 v[34:35], v[54:55], v[34:35]
	v_exp_f32_e32 v54, v1
	v_mul_f32_e32 v1, 0x3fb8aa3b, v2
	v_mul_f32_e32 v2, 0xbfb8aa3b, v2
	v_pk_add_f32 v[52:53], v[30:31], 1.0 op_sel_hi:[1,0] neg_lo:[1,0] neg_hi:[1,0]
	v_exp_f32_e32 v30, v5
	v_exp_f32_e32 v5, v2
	v_sub_f32_e32 v2, v7, v3
	v_mul_f32_e32 v3, 0x3fb8aa3b, v2
	v_exp_f32_e32 v31, v3
	v_mul_f32_e32 v2, 0xbfb8aa3b, v2
	s_waitcnt lgkmcnt(0)
	v_sub_f32_e32 v3, v16, v12
	v_exp_f32_e32 v55, v2
	v_mul_f32_e32 v2, 0x3fb8aa3b, v3
	v_mul_f32_e32 v3, 0xbfb8aa3b, v3
	v_exp_f32_e32 v6, v3
	v_sub_f32_e32 v3, v17, v13
	v_mul_f32_e32 v7, 0x3fb8aa3b, v3
	v_exp_f32_e32 v12, v7
	v_sub_f32_e32 v7, v18, v14
	v_sub_f32_e32 v14, v19, v15
	v_sub_f32_e32 v4, v4, v0
	v_mul_f32_e32 v13, 0x3fb8aa3b, v14
	v_mul_f32_e32 v0, 0x3fb8aa3b, v4
	v_mul_f32_e32 v3, 0xbfb8aa3b, v3
	v_exp_f32_e32 v13, v13
	v_exp_f32_e32 v0, v0
	v_exp_f32_e32 v1, v1
	v_exp_f32_e32 v16, v3
	v_mul_f32_e32 v3, 0x3fb8aa3b, v7
	v_exp_f32_e32 v2, v2
	v_exp_f32_e32 v3, v3
	v_mul_f32_e32 v14, 0xbfb8aa3b, v14
	v_pk_mul_f32 v[12:13], v[36:37], v[12:13]
	v_mul_f32_e32 v4, 0xbfb8aa3b, v4
	v_exp_f32_e32 v17, v14
	v_pk_mul_f32 v[0:1], v[44:45], v[0:1]
	v_pk_mul_f32 v[14:15], v[38:39], v[30:31]
	v_bfe_u32 v18, v13, 16, 1
	v_bfe_u32 v19, v12, 16, 1
	v_exp_f32_e32 v4, v4
	v_mul_f32_e32 v7, 0xbfb8aa3b, v7
	v_pk_mul_f32 v[2:3], v[48:49], v[2:3]
	v_bfe_u32 v30, v15, 16, 1
	v_bfe_u32 v31, v14, 16, 1
	v_add3_u32 v12, v12, v19, s54
	v_add3_u32 v13, v13, v18, s54
	v_bfe_u32 v18, v0, 16, 1
	v_bfe_u32 v19, v1, 16, 1
	v_exp_f32_e32 v7, v7
	v_add3_u32 v14, v14, v31, s54
	v_add3_u32 v15, v15, v30, s54
	v_bfe_u32 v30, v2, 16, 1
	v_bfe_u32 v31, v3, 16, 1
	v_add3_u32 v1, v1, v19, s54
	v_add3_u32 v0, v0, v18, s54
	v_add3_u32 v3, v3, v31, s54
	v_add3_u32 v2, v2, v30, s54
	v_lshrrev_b32_e32 v0, 16, v0
	v_lshrrev_b32_e32 v1, 16, v1
	v_lshrrev_b32_e32 v2, 16, v2
	v_lshrrev_b32_e32 v3, 16, v3
	v_and_or_b32 v1, v15, s33, v1
	v_and_or_b32 v0, v14, s33, v0
	v_pk_mul_f32 v[14:15], v[66:67], v[16:17]
	v_and_or_b32 v3, v13, s33, v3
	v_and_or_b32 v2, v12, s33, v2
	v_pk_mul_f32 v[4:5], v[62:63], v[4:5]
	v_pk_mul_f32 v[12:13], v[64:65], v[54:55]
	v_bfe_u32 v16, v15, 16, 1
	v_pk_mul_f32 v[6:7], v[46:47], v[6:7]
	v_bfe_u32 v17, v14, 16, 1
	v_bfe_u32 v18, v13, 16, 1
	v_bfe_u32 v19, v12, 16, 1
	v_add3_u32 v15, v15, v16, s54
	v_bfe_u32 v16, v4, 16, 1
	v_add3_u32 v12, v12, v19, s54
	v_add3_u32 v13, v13, v18, s54
	v_add3_u32 v14, v14, v17, s54
	v_bfe_u32 v17, v5, 16, 1
	v_bfe_u32 v18, v6, 16, 1
	v_bfe_u32 v19, v7, 16, 1
	v_add3_u32 v4, v4, v16, s54
	v_add_u32_e32 v68, 0, v156
	v_add3_u32 v7, v7, v19, s54
	v_add3_u32 v6, v6, v18, s54
	v_add3_u32 v5, v5, v17, s54
	v_lshrrev_b32_e32 v4, 16, v4
	v_mul_lo_u32 v30, v24, s29
	v_lshrrev_b32_e32 v5, 16, v5
	v_lshrrev_b32_e32 v6, 16, v6
	v_lshrrev_b32_e32 v7, 16, v7
	v_and_or_b32 v4, v12, s33, v4
	v_add_u32_e32 v12, v68, v30
	v_and_or_b32 v7, v15, s33, v7
	v_and_or_b32 v6, v14, s33, v6
	v_and_or_b32 v5, v13, s33, v5
	ds_write_b128 v12, v[0:3]
	ds_write_b128 v12, v[4:7] offset:17408
	ds_read_b128 v[0:3], v9
	ds_read_b128 v[4:7], v42
	ds_read_b128 v[12:15], v9 offset:16
	ds_read_b128 v[16:19], v42 offset:16
	v_pk_mul_f32 v[36:37], v[58:59], v[56:57]
	v_pk_mul_f32 v[28:29], v[60:61], v[28:29]
	v_pk_add_f32 v[22:23], v[22:23], 1.0 op_sel_hi:[1,0] neg_lo:[1,0] neg_hi:[1,0]
	s_waitcnt lgkmcnt(2)
	v_sub_f32_e32 v1, v5, v1
	v_mul_f32_e32 v5, 0x3fb8aa3b, v1
	v_mul_f32_e32 v1, 0xbfb8aa3b, v1
	v_sub_f32_e32 v2, v6, v2
	v_exp_f32_e32 v42, v1
	v_mul_f32_e32 v1, 0x3fb8aa3b, v2
	v_mul_f32_e32 v2, 0xbfb8aa3b, v2
	v_exp_f32_e32 v38, v5
	v_exp_f32_e32 v5, v2
	v_sub_f32_e32 v2, v7, v3
	v_mul_f32_e32 v3, 0x3fb8aa3b, v2
	v_exp_f32_e32 v39, v3
	v_mul_f32_e32 v2, 0xbfb8aa3b, v2
	s_waitcnt lgkmcnt(0)
	v_sub_f32_e32 v3, v16, v12
	v_exp_f32_e32 v43, v2
	v_mul_f32_e32 v2, 0x3fb8aa3b, v3
	v_mul_f32_e32 v3, 0xbfb8aa3b, v3
	v_exp_f32_e32 v6, v3
	v_sub_f32_e32 v3, v17, v13
	v_mul_f32_e32 v7, 0x3fb8aa3b, v3
	v_exp_f32_e32 v12, v7
	v_mul_f32_e32 v3, 0xbfb8aa3b, v3
	v_sub_f32_e32 v7, v18, v14
	v_sub_f32_e32 v9, v19, v15
	v_sub_f32_e32 v4, v4, v0
	v_exp_f32_e32 v16, v3
	v_mul_f32_e32 v3, 0x3fb8aa3b, v7
	v_mul_f32_e32 v13, 0x3fb8aa3b, v9
	v_mul_f32_e32 v0, 0x3fb8aa3b, v4
	v_exp_f32_e32 v2, v2
	v_exp_f32_e32 v3, v3
	v_exp_f32_e32 v13, v13
	v_exp_f32_e32 v0, v0
	v_exp_f32_e32 v1, v1
	v_pk_mul_f32 v[14:15], v[34:35], v[38:39]
	v_mul_f32_e32 v7, 0xbfb8aa3b, v7
	v_mul_f32_e32 v9, 0xbfb8aa3b, v9
	v_pk_mul_f32 v[2:3], v[36:37], v[2:3]
	v_pk_mul_f32 v[12:13], v[28:29], v[12:13]
	v_bfe_u32 v19, v15, 16, 1
	v_mul_f32_e32 v4, 0xbfb8aa3b, v4
	v_exp_f32_e32 v7, v7
	v_exp_f32_e32 v17, v9
	v_pk_mul_f32 v[0:1], v[50:51], v[0:1]
	v_bfe_u32 v9, v13, 16, 1
	v_bfe_u32 v18, v12, 16, 1
	v_add3_u32 v15, v15, v19, s54
	v_bfe_u32 v19, v2, 16, 1
	v_exp_f32_e32 v4, v4
	v_bfe_u32 v28, v14, 16, 1
	v_add3_u32 v12, v12, v18, s54
	v_add3_u32 v9, v13, v9, s54
	v_bfe_u32 v13, v0, 16, 1
	v_bfe_u32 v18, v1, 16, 1
	v_add3_u32 v2, v2, v19, s54
	v_add3_u32 v14, v14, v28, s54
	v_bfe_u32 v28, v3, 16, 1
	v_add3_u32 v1, v1, v18, s54
	v_add3_u32 v0, v0, v13, s54
	v_lshrrev_b32_e32 v2, 16, v2
	v_pk_add_f32 v[32:33], v[32:33], 1.0 op_sel_hi:[1,0] neg_lo:[1,0] neg_hi:[1,0]
	v_add3_u32 v3, v3, v28, s54
	v_lshrrev_b32_e32 v0, 16, v0
	v_lshrrev_b32_e32 v1, 16, v1
	v_and_or_b32 v2, v12, s33, v2
	v_pk_mul_f32 v[12:13], v[22:23], v[42:43]
	v_pk_add_f32 v[20:21], v[20:21], 1.0 op_sel_hi:[1,0] neg_lo:[1,0] neg_hi:[1,0]
	v_lshrrev_b32_e32 v3, 16, v3
	v_and_or_b32 v1, v15, s33, v1
	v_and_or_b32 v0, v14, s33, v0
	v_pk_mul_f32 v[6:7], v[32:33], v[6:7]
	v_pk_mul_f32 v[14:15], v[52:53], v[16:17]
	v_bfe_u32 v18, v12, 16, 1
	s_ashr_i32 s15, s14, 31
	s_mul_i32 s19, s14, 0x1e00
	v_and_or_b32 v3, v9, s33, v3
	v_pk_mul_f32 v[4:5], v[20:21], v[4:5]
	v_bfe_u32 v9, v15, 16, 1
	v_bfe_u32 v16, v14, 16, 1
	v_bfe_u32 v17, v13, 16, 1
	v_add3_u32 v12, v12, v18, s54
	v_bfe_u32 v18, v7, 16, 1
	s_mul_hi_i32 s18, s14, 0x1e00
	s_add_u32 s19, s1, s19
	v_add3_u32 v13, v13, v17, s54
	v_add3_u32 v14, v14, v16, s54
	v_add3_u32 v9, v15, v9, s54
	v_bfe_u32 v15, v4, 16, 1
	v_bfe_u32 v16, v5, 16, 1
	v_bfe_u32 v17, v6, 16, 1
	v_add3_u32 v7, v7, v18, s54
	s_addc_u32 s22, s22, s18
	s_lshl_b32 s1, s0, 1
	v_add3_u32 v6, v6, v17, s54
	v_add3_u32 v5, v5, v16, s54
	v_add3_u32 v4, v4, v15, s54
	v_lshrrev_b32_e32 v7, 16, v7
	v_mul_lo_u32 v31, v26, s29
	s_add_u32 s18, s19, s1
	v_lshrrev_b32_e32 v4, 16, v4
	v_lshrrev_b32_e32 v5, 16, v5
	v_lshrrev_b32_e32 v6, 16, v6
	v_and_or_b32 v7, v9, s33, v7
	v_add_u32_e32 v9, v68, v31
	s_addc_u32 s19, s22, 0
	v_and_or_b32 v6, v14, s33, v6
	v_and_or_b32 v5, v13, s33, v5
	v_and_or_b32 v4, v12, s33, v4
	ds_write_b128 v9, v[0:3]
	ds_write_b128 v9, v[4:7] offset:17408
	v_lshl_add_u64 v[0:1], s[18:19], 0, v[156:157]
	v_lshl_add_u64 v[0:1], v[0:1], 0, s[48:49]
	v_mad_i64_i32 v[2:3], s[18:19], v24, s83, v[0:1]
	s_waitcnt lgkmcnt(0)
	s_barrier
	v_mov_b32_e32 v12, v70
	v_mov_b32_e32 v13, v71
	v_mov_b32_e32 v14, v72
	v_mov_b32_e32 v15, v73
	v_mad_i64_i32 v[0:1], s[18:19], v26, s83, v[0:1]
	v_mov_b32_e32 v16, v74
	v_mov_b32_e32 v17, v75
	v_mov_b32_e32 v18, v76
	v_mov_b32_e32 v19, v77
	v_ashrrev_i32_e32 v9, 31, v8
	v_lshlrev_b32_e32 v2, 1, v11
	v_lshlrev_b64 v[0:1], 8, v[8:9]
	v_and_b32_e32 v2, 0xf0, v2
	v_or_b32_e32 v0, v0, v2
	v_lshl_add_u64 v[0:1], s[16:17], 0, v[0:1]
	v_lshl_add_u64 v[0:1], v[0:1], 0, s[4:5]
	v_mov_b32_e32 v20, v82
	v_mov_b32_e32 v21, v83
	v_mov_b32_e32 v22, v84
	v_mov_b32_e32 v23, v85
	v_mov_b32_e32 v34, v86
	v_mov_b32_e32 v35, v87
	v_mov_b32_e32 v36, v88
	v_mov_b32_e32 v37, v89
	v_ashrrev_i32_e32 v11, 31, v10
	v_lshlrev_b64 v[0:1], 8, v[10:11]
	v_or_b32_e32 v0, v0, v2
	v_lshl_add_u64 v[0:1], s[16:17], 0, v[0:1]
	v_lshl_add_u64 v[4:5], v[0:1], 0, s[4:5]
	v_mov_b32_e32 v0, v94
	v_mov_b32_e32 v1, v95
	v_mov_b32_e32 v2, v96
	v_mov_b32_e32 v3, v97
	s_nop 0
	v_mov_b32_e32 v4, v98
	v_mov_b32_e32 v5, v99
	v_mov_b32_e32 v6, v100
	v_mov_b32_e32 v7, v101
	v_lshlrev_b32_e32 v8, 4, v25
	v_and_b32_e32 v8, 0xf0, v8
	v_add_u32_e32 v8, s43, v8
	v_ashrrev_i32_e32 v10, 3, v40
	v_add_u32_e32 v9, v8, v30
	v_lshlrev_b32_e32 v11, 2, v10
	v_add_u32_e32 v8, v8, v31
	s_add_i32 s16, 0, 0x1fc00
	v_readfirstlane_b32 s18, v40
	v_and_b32_e32 v32, 15, v25
	s_bfe_u32 s17, s18, 0x10006
	s_lshl_b32 s19, s17, 6
	ds_write_b128 v9, v[12:15]
	v_and_b32_e32 v12, -8, v11
	v_or_b32_e32 v11, 4, v11
	ds_write_b128 v8, v[16:19]
	v_add_u32_e32 v12, s16, v12
	v_add_u32_e32 v11, s16, v11
	ds_read_b32 v12, v12
	ds_read_b32 v11, v11
	v_and_b32_e32 v8, 12, v25
	v_lshlrev_b32_e32 v9, 5, v25
	v_and_or_b32 v8, v9, s44, v8
	v_lshlrev_b32_e32 v9, 16, v20
	v_lshlrev_b32_e32 v14, 16, v34
	s_waitcnt lgkmcnt(1)
	v_mul_f32_e32 v9, v12, v9
	s_waitcnt lgkmcnt(0)
	v_mul_f32_e32 v14, v11, v14
	v_bfe_u32 v28, v9, 16, 1
	v_add3_u32 v9, v9, v28, s54
	v_bfe_u32 v28, v14, 16, 1
	v_lshrrev_b32_e32 v9, 16, v9
	v_add3_u32 v14, v14, v28, s54
	v_and_or_b32 v9, v14, s33, v9
	v_and_b32_e32 v14, 0xffff0000, v20
	v_and_b32_e32 v13, -8, v10
	v_and_b32_e32 v20, 0xffff0000, v34
	v_mul_f32_e32 v14, v12, v14
	v_bitop3_b32 v17, v8, v13, 40 bitop3:0x6c
	v_lshlrev_b32_e32 v10, 1, v10
	v_ashrrev_i32_e32 v18, 3, v27
	v_mul_f32_e32 v20, v11, v20
	v_bfe_u32 v28, v14, 16, 1
	v_mad_u32_u24 v15, v8, s29, 0
	v_lshlrev_b32_e32 v17, 1, v17
	v_and_b32_e32 v10, 12, v10
	v_lshlrev_b32_e32 v19, 2, v18
	v_add3_u32 v14, v14, v28, s54
	v_bfe_u32 v28, v20, 16, 1
	v_add3_u32 v17, v15, v17, v10
	v_and_b32_e32 v27, -8, v19
	v_or_b32_e32 v19, 4, v19
	v_lshrrev_b32_e32 v14, 16, v14
	v_add3_u32 v20, v20, v28, s54
	v_add_u32_e32 v27, s16, v27
	v_add_u32_e32 v19, s16, v19
	v_and_or_b32 v14, v20, s33, v14
	v_add_u32_e32 v17, 0xf400, v17
	ds_read_b32 v27, v27
	ds_read_b32 v19, v19
	ds_write2_b32 v17, v9, v14 offset1:68
	v_lshlrev_b32_e32 v9, 16, v21
	v_lshlrev_b32_e32 v14, 16, v35
	v_mul_f32_e32 v9, v12, v9
	v_mul_f32_e32 v14, v11, v14
	v_bfe_u32 v20, v9, 16, 1
	v_add3_u32 v9, v9, v20, s54
	v_bfe_u32 v20, v14, 16, 1
	v_lshrrev_b32_e32 v9, 16, v9
	v_add3_u32 v14, v14, v20, s54
	v_and_or_b32 v9, v14, s33, v9
	v_and_b32_e32 v14, 0xffff0000, v21
	v_and_b32_e32 v20, 0xffff0000, v35
	v_mul_f32_e32 v14, v12, v14
	v_mul_f32_e32 v20, v11, v20
	v_bfe_u32 v21, v14, 16, 1
	v_add3_u32 v14, v14, v21, s54
	v_bfe_u32 v21, v20, 16, 1
	v_lshrrev_b32_e32 v14, 16, v14
	v_add3_u32 v20, v20, v21, s54
	v_and_or_b32 v14, v20, s33, v14
	ds_write2_b32 v17, v9, v14 offset0:136 offset1:204
	v_lshlrev_b32_e32 v14, 16, v22
	v_lshlrev_b32_e32 v17, 16, v36
	v_mul_f32_e32 v14, v12, v14
	v_or_b32_e32 v9, 16, v8
	v_mul_f32_e32 v17, v11, v17
	v_bfe_u32 v28, v14, 16, 1
	v_bitop3_b32 v13, v9, v13, 56 bitop3:0x6c
	v_add3_u32 v14, v14, v28, s54
	v_bfe_u32 v28, v17, 16, 1
	v_mad_u32_u24 v20, v9, s29, 0
	v_lshlrev_b32_e32 v13, 1, v13
	v_lshrrev_b32_e32 v14, 16, v14
	v_add3_u32 v17, v17, v28, s54
	v_add3_u32 v21, v20, v13, v10
	v_and_or_b32 v14, v17, s33, v14
	v_add_u32_e32 v16, 0xf400, v15
	ds_write_b32 v21, v14 offset:62464
	v_and_b32_e32 v14, 0xffff0000, v22
	v_and_b32_e32 v17, 0xffff0000, v36
	v_add3_u32 v10, v16, v13, v10
	v_mul_f32_e32 v13, v12, v14
	v_mul_f32_e32 v14, v11, v17
	v_bfe_u32 v17, v13, 16, 1
	v_add3_u32 v13, v13, v17, s54
	v_bfe_u32 v17, v14, 16, 1
	v_lshrrev_b32_e32 v13, 16, v13
	v_add3_u32 v14, v14, v17, s54
	v_and_or_b32 v13, v14, s33, v13
	v_lshlrev_b32_e32 v14, 16, v23
	v_lshlrev_b32_e32 v17, 16, v37
	v_mul_f32_e32 v14, v12, v14
	v_mul_f32_e32 v17, v11, v17
	v_bfe_u32 v21, v14, 16, 1
	v_add3_u32 v14, v14, v21, s54
	v_bfe_u32 v21, v17, 16, 1
	v_lshrrev_b32_e32 v14, 16, v14
	v_add3_u32 v17, v17, v21, s54
	v_and_or_b32 v14, v17, s33, v14
	v_add_u32_e32 v17, 0x1000, v10
	ds_write2_b32 v17, v13, v14 offset0:132 offset1:200
	v_and_b32_e32 v13, 0xffff0000, v23
	v_and_b32_e32 v14, 0xffff0000, v37
	v_mul_f32_e32 v12, v12, v13
	v_mul_f32_e32 v11, v11, v14
	v_bfe_u32 v13, v12, 16, 1
	v_add3_u32 v12, v12, v13, s54
	v_bfe_u32 v13, v11, 16, 1
	v_lshrrev_b32_e32 v12, 16, v12
	v_add3_u32 v11, v11, v13, s54
	v_and_or_b32 v11, v11, s33, v12
	ds_write_b32 v10, v11 offset:5168
	v_lshlrev_b32_e32 v11, 16, v0
	v_lshlrev_b32_e32 v12, 16, v4
	s_waitcnt lgkmcnt(6)
	v_mul_f32_e32 v11, v27, v11
	s_waitcnt lgkmcnt(5)
	v_mul_f32_e32 v12, v19, v12
	v_bfe_u32 v14, v11, 16, 1
	v_add3_u32 v11, v11, v14, s54
	v_bfe_u32 v14, v12, 16, 1
	v_and_b32_e32 v0, 0xffff0000, v0
	v_and_b32_e32 v10, -8, v18
	v_lshrrev_b32_e32 v11, 16, v11
	v_add3_u32 v12, v12, v14, s54
	v_and_b32_e32 v4, 0xffff0000, v4
	v_mul_f32_e32 v0, v27, v0
	v_bitop3_b32 v8, v8, v10, 40 bitop3:0x6c
	v_lshlrev_b32_e32 v13, 1, v18
	v_and_or_b32 v11, v12, s33, v11
	v_mul_f32_e32 v4, v19, v4
	v_bfe_u32 v12, v0, 16, 1
	v_lshlrev_b32_e32 v8, 1, v8
	v_and_b32_e32 v13, 12, v13
	v_add3_u32 v0, v0, v12, s54
	v_bfe_u32 v12, v4, 16, 1
	v_add3_u32 v8, v15, v8, v13
	v_lshrrev_b32_e32 v0, 16, v0
	v_add3_u32 v4, v4, v12, s54
	v_and_or_b32 v0, v4, s33, v0
	v_add_u32_e32 v4, 0xf400, v8
	ds_write2_b32 v4, v11, v0 offset1:68
	v_lshlrev_b32_e32 v0, 16, v1
	v_lshlrev_b32_e32 v8, 16, v5
	v_mul_f32_e32 v0, v27, v0
	v_mul_f32_e32 v8, v19, v8
	v_bfe_u32 v11, v0, 16, 1
	v_add3_u32 v0, v0, v11, s54
	v_bfe_u32 v11, v8, 16, 1
	v_and_b32_e32 v1, 0xffff0000, v1
	v_lshrrev_b32_e32 v0, 16, v0
	v_add3_u32 v8, v8, v11, s54
	v_and_b32_e32 v5, 0xffff0000, v5
	v_mul_f32_e32 v1, v27, v1
	v_and_or_b32 v0, v8, s33, v0
	v_mul_f32_e32 v5, v19, v5
	v_bfe_u32 v8, v1, 16, 1
	v_add3_u32 v1, v1, v8, s54
	v_bfe_u32 v8, v5, 16, 1
	v_lshrrev_b32_e32 v1, 16, v1
	v_add3_u32 v5, v5, v8, s54
	v_and_or_b32 v1, v5, s33, v1
	ds_write2_b32 v4, v0, v1 offset0:136 offset1:204
	v_lshlrev_b32_e32 v0, 16, v2
	v_lshlrev_b32_e32 v1, 16, v6
	v_mul_f32_e32 v0, v27, v0
	v_mul_f32_e32 v1, v19, v1
	v_bfe_u32 v8, v0, 16, 1
	v_bitop3_b32 v4, v9, v10, 56 bitop3:0x6c
	v_add3_u32 v0, v0, v8, s54
	v_bfe_u32 v8, v1, 16, 1
	v_lshlrev_b32_e32 v4, 1, v4
	v_lshrrev_b32_e32 v0, 16, v0
	v_add3_u32 v1, v1, v8, s54
	v_add3_u32 v5, v20, v4, v13
	v_and_or_b32 v0, v1, s33, v0
	ds_write_b32 v5, v0 offset:62464
	v_and_b32_e32 v0, 0xffff0000, v2
	v_and_b32_e32 v1, 0xffff0000, v6
	v_mul_f32_e32 v0, v27, v0
	v_add3_u32 v2, v16, v4, v13
	v_mul_f32_e32 v1, v19, v1
	v_bfe_u32 v4, v0, 16, 1
	v_add3_u32 v0, v0, v4, s54
	v_bfe_u32 v4, v1, 16, 1
	v_lshrrev_b32_e32 v0, 16, v0
	v_add3_u32 v1, v1, v4, s54
	v_and_or_b32 v0, v1, s33, v0
	v_lshlrev_b32_e32 v1, 16, v3
	v_lshlrev_b32_e32 v4, 16, v7
	v_mul_f32_e32 v1, v27, v1
	v_mul_f32_e32 v4, v19, v4
	v_bfe_u32 v5, v1, 16, 1
	v_add3_u32 v1, v1, v5, s54
	v_bfe_u32 v5, v4, 16, 1
	v_lshrrev_b32_e32 v1, 16, v1
	v_add3_u32 v4, v4, v5, s54
	v_and_or_b32 v1, v4, s33, v1
	v_add_u32_e32 v4, 0x1000, v2
	ds_write2_b32 v4, v0, v1 offset0:132 offset1:200
	v_and_b32_e32 v0, 0xffff0000, v3
	v_and_b32_e32 v1, 0xffff0000, v7
	v_mul_f32_e32 v0, v27, v0
	v_mul_f32_e32 v1, v19, v1
	v_bfe_u32 v3, v0, 16, 1
	v_add3_u32 v0, v0, v3, s54
	v_bfe_u32 v3, v1, 16, 1
	v_lshrrev_b32_e32 v0, 16, v0
	v_add3_u32 v1, v1, v3, s54
	s_ashr_i32 s16, s18, 3
	v_and_or_b32 v0, v1, s33, v0
	v_bfe_u32 v22, v25, 4, 2
	v_bfi_b32 v23, -16, s16, v25
	ds_write_b32 v2, v0 offset:5168
	v_mul_lo_u32 v0, v23, s29
	v_lshlrev_b32_e32 v17, 4, v22
	v_add3_u32 v27, 0, v0, v17
	ds_read_b128 v[0:3], v27
	v_lshl_or_b32 v16, s17, 5, v32
	v_mul_u32_u24_e32 v4, 0x110, v16
	v_add3_u32 v28, 0, v4, v17
	ds_read_b128 v[4:7], v28 offset:17408
	ds_read_b128 v[8:11], v27 offset:64
	ds_read_b128 v[12:15], v28 offset:17472
	s_waitcnt lgkmcnt(2)
	v_mfma_f32_16x16x32_bf16 v[4:7], v[0:3], v[4:7], 0
	ds_read_b128 v[18:21], v28 offset:21760
	ds_read_b128 v[34:37], v28 offset:21824
	s_and_b32 s18, s16, -16
	v_lshl_or_b32 v33, v22, 2, s18
	s_waitcnt lgkmcnt(2)
	v_mfma_f32_16x16x32_bf16 v[4:7], v[8:11], v[12:15], v[4:7]
	ds_read_b128 v[12:15], v27 offset:128
	v_cmp_le_i32_e32 vcc, v16, v33
	s_waitcnt lgkmcnt(2)
	v_mfma_f32_16x16x32_bf16 v[0:3], v[0:3], v[18:21], 0
	s_waitcnt lgkmcnt(1)
	v_mfma_f32_16x16x32_bf16 v[0:3], v[8:11], v[34:37], v[0:3]
	ds_read_b128 v[8:11], v28 offset:17536
	ds_read_b128 v[18:21], v27 offset:192
	ds_read_b128 v[34:37], v28 offset:17600
	s_waitcnt lgkmcnt(2)
	v_mfma_f32_16x16x32_bf16 v[4:7], v[12:15], v[8:11], v[4:7]
	ds_read_b128 v[8:11], v28 offset:21888
	ds_read_b128 v[38:41], v28 offset:21952
	v_lshrrev_b32_e32 v28, 4, v25
	v_bfe_u32 v25, v25, 3, 1
	s_waitcnt lgkmcnt(1)
	v_mfma_f32_16x16x32_bf16 v[0:3], v[12:15], v[8:11], v[0:3]
	v_or_b32_e32 v8, 16, v16
	v_lshlrev_b32_e32 v10, 1, v16
	v_mfma_f32_16x16x32_bf16 v[4:7], v[18:21], v[34:37], v[4:7]
	v_or_b32_e32 v34, 48, v32
	v_lshrrev_b32_e32 v54, 3, v34
	s_waitcnt lgkmcnt(0)
	v_mfma_f32_16x16x32_bf16 v[0:3], v[18:21], v[38:41], v[0:3]
	v_or_b32_e32 v18, 32, v32
	s_nop 2
	v_cndmask_b32_e32 v4, 0, v4, vcc
	v_bfe_u32 v9, v4, 16, 1
	v_add3_u32 v4, v4, v9, s54
	v_mul_lo_u32 v9, v33, s85
	v_cmp_le_i32_e32 vcc, v8, v33
	v_add3_u32 v9, 0, v9, v10
	ds_write_b16_d16_hi v9, v4 offset:34816
	v_cndmask_b32_e32 v0, 0, v0, vcc
	v_bfe_u32 v4, v0, 16, 1
	v_add3_u32 v0, v0, v4, s54
	ds_write_b16_d16_hi v9, v0 offset:34848
	v_or_b32_e32 v0, 1, v33
	v_cmp_le_i32_e32 vcc, v16, v0
	v_lshrrev_b32_e32 v51, 3, v18
	v_bitop3_b32 v18, v51, v28, 3 bitop3:0x78
	v_cndmask_b32_e32 v4, 0, v5, vcc
	v_cmp_le_i32_e32 vcc, v8, v0
	v_bfe_u32 v5, v4, 16, 1
	v_add3_u32 v4, v4, v5, s54
	v_cndmask_b32_e32 v0, 0, v1, vcc
	v_bfe_u32 v1, v0, 16, 1
	v_add3_u32 v0, v0, v1, s54
	ds_write_b16_d16_hi v9, v0 offset:34992
	v_or_b32_e32 v0, 2, v33
	v_cmp_le_i32_e32 vcc, v16, v0
	ds_write_b16_d16_hi v9, v4 offset:34960
	v_lshlrev_b32_e32 v52, 4, v18
	v_cndmask_b32_e32 v1, 0, v6, vcc
	v_bfe_u32 v4, v1, 16, 1
	v_cmp_le_i32_e32 vcc, v8, v0
	v_add3_u32 v1, v1, v4, s54
	ds_write_b16_d16_hi v9, v1 offset:35104
	v_cndmask_b32_e32 v0, 0, v2, vcc
	v_bfe_u32 v1, v0, 16, 1
	v_add3_u32 v0, v0, v1, s54
	ds_write_b16_d16_hi v9, v0 offset:35136
	v_or_b32_e32 v0, 3, v33
	v_cmp_le_i32_e32 vcc, v16, v0
	v_or_b32_e32 v16, s19, v32
	v_mad_u32_u24 v29, v16, s29, 0
	v_cndmask_b32_e32 v1, 0, v7, vcc
	v_bfe_u32 v2, v1, 16, 1
	v_cmp_le_i32_e32 vcc, v8, v0
	v_add3_u32 v1, v1, v2, s54
	ds_write_b16_d16_hi v9, v1 offset:35248
	v_cndmask_b32_e32 v0, 0, v3, vcc
	v_bfe_u32 v1, v0, 16, 1
	v_add3_u32 v0, v0, v1, s54
	v_or_b32_e32 v8, 16, v32
	ds_write_b16_d16_hi v9, v0 offset:35280
	s_waitcnt lgkmcnt(0)
	s_barrier
	ds_read_b128 v[0:3], v27
	v_lshrrev_b32_e32 v48, 3, v8
	v_bitop3_b32 v4, v25, v28, 3 bitop3:0x78
	v_bitop3_b32 v8, v48, v28, 3 bitop3:0x78
	v_bitop3_b32 v28, v54, v28, 3 bitop3:0x78
	v_lshlrev_b32_e32 v46, 4, v4
	v_add_u32_e32 v47, 0x1100, v29
	v_lshlrev_b32_e32 v49, 4, v8
	v_add_u32_e32 v50, 0x2200, v29
	v_add_u32_e32 v53, 0x3300, v29
	v_lshlrev_b32_e32 v28, 4, v28
	v_add_u32_e32 v4, v29, v46
	v_add_u32_e32 v8, v47, v49
	v_add_u32_e32 v18, v50, v52
	v_add_u32_e32 v34, v53, v28
	ds_read_b128 v[4:7], v4 offset:62464
	ds_read_b128 v[8:11], v8 offset:62464
	ds_read_b128 v[12:15], v27 offset:64
	ds_read_b128 v[18:21], v18 offset:62464
	ds_read_b128 v[34:37], v34 offset:62464
	s_waitcnt lgkmcnt(4)
	v_mfma_f32_16x16x32_bf16 v[4:7], v[0:3], v[4:7], 0
	v_bitop3_b32 v38, v48, v22, 4 bitop3:0x1e
	v_lshlrev_b32_e32 v56, 4, v38
	v_add_u32_e32 v38, v47, v56
	s_waitcnt lgkmcnt(3)
	v_mfma_f32_16x16x32_bf16 v[8:11], v[0:3], v[8:11], 0
	ds_read_b128 v[38:41], v38 offset:62464
	v_cmp_eq_u32_e32 vcc, 0, v32
	s_waitcnt lgkmcnt(2)
	v_mfma_f32_16x16x32_bf16 v[18:21], v[0:3], v[18:21], 0
	s_waitcnt lgkmcnt(1)
	v_mfma_f32_16x16x32_bf16 v[0:3], v[0:3], v[34:37], 0
	v_bitop3_b32 v34, v22, v25, 4 bitop3:0x36
	v_lshlrev_b32_e32 v55, 4, v34
	v_add_u32_e32 v34, v29, v55
	ds_read_b128 v[34:37], v34 offset:62464
	s_waitcnt lgkmcnt(1)
	v_mfma_f32_16x16x32_bf16 v[8:11], v[12:15], v[38:41], v[8:11]
	v_bitop3_b32 v38, v54, v22, 4 bitop3:0x1e
	v_lshlrev_b32_e32 v58, 4, v38
	v_add_u32_e32 v38, v53, v58
	s_waitcnt lgkmcnt(0)
	v_mfma_f32_16x16x32_bf16 v[4:7], v[12:15], v[34:37], v[4:7]
	v_bitop3_b32 v34, v51, v22, 4 bitop3:0x1e
	v_lshlrev_b32_e32 v57, 4, v34
	v_add_u32_e32 v34, v50, v57
	ds_read_b128 v[34:37], v34 offset:62464
	ds_read_b128 v[38:41], v38 offset:62464
	s_waitcnt lgkmcnt(1)
	v_mfma_f32_16x16x32_bf16 v[18:21], v[12:15], v[34:37], v[18:21]
	ds_read_b128 v[34:37], v27 offset:128
	s_waitcnt lgkmcnt(1)
	v_mfma_f32_16x16x32_bf16 v[0:3], v[12:15], v[38:41], v[0:3]
	v_bitop3_b32 v12, v22, v25, 8 bitop3:0x36
	v_lshl_add_u32 v12, v12, 4, v29
	ds_read_b128 v[12:15], v12 offset:62464
	v_bitop3_b32 v38, v48, v22, 8 bitop3:0x1e
	s_waitcnt lgkmcnt(0)
	v_mfma_f32_16x16x32_bf16 v[4:7], v[34:37], v[12:15], v[4:7]
	v_bitop3_b32 v12, v51, v22, 8 bitop3:0x1e
	v_lshl_add_u32 v38, v38, 4, v47
	v_lshl_add_u32 v12, v12, 4, v50
	ds_read_b128 v[38:41], v38 offset:62464
	ds_read_b128 v[42:45], v27 offset:192
	ds_read_b128 v[12:15], v12 offset:62464
	v_bitop3_b32 v27, v54, v22, 8 bitop3:0x1e
	v_lshl_add_u32 v27, v27, 4, v53
	s_waitcnt lgkmcnt(2)
	v_mfma_f32_16x16x32_bf16 v[8:11], v[34:37], v[38:41], v[8:11]
	ds_read_b128 v[38:41], v27 offset:62464
	s_waitcnt lgkmcnt(1)
	v_mfma_f32_16x16x32_bf16 v[12:15], v[34:37], v[12:15], v[18:21]
	s_nop 2
	v_bitop3_b32 v18, v22, v25, 12 bitop3:0x36
	v_lshl_add_u32 v18, v18, 4, v29
	ds_read_b128 v[18:21], v18 offset:62464
	v_bitop3_b32 v25, v48, v22, 12 bitop3:0x1e
	v_lshl_add_u32 v25, v25, 4, v47
	s_waitcnt lgkmcnt(1)
	v_mfma_f32_16x16x32_bf16 v[0:3], v[34:37], v[38:41], v[0:3]
	ds_read_b128 v[34:37], v25 offset:62464
	s_waitcnt lgkmcnt(1)
	v_mfma_f32_16x16x32_bf16 v[4:7], v[42:45], v[18:21], v[4:7]
	v_bitop3_b32 v18, v51, v22, 12 bitop3:0x1e
	v_lshl_add_u32 v18, v18, 4, v50
	ds_read_b128 v[18:21], v18 offset:62464
	v_bitop3_b32 v22, v54, v22, 12 bitop3:0x1e
	v_lshl_add_u32 v22, v22, 4, v53
	s_waitcnt lgkmcnt(1)
	v_mfma_f32_16x16x32_bf16 v[8:11], v[42:45], v[34:37], v[8:11]
	ds_read_b128 v[34:37], v22 offset:62464
	s_waitcnt lgkmcnt(1)
	v_mfma_f32_16x16x32_bf16 v[12:15], v[42:45], v[18:21], v[12:15]
	v_mul_lo_u32 v18, v23, s85
	v_add3_u32 v22, 0, v18, v17
	ds_read_b128 v[18:21], v22 offset:34816
	v_mul_u32_u24_e32 v23, 0x90, v16
	v_add3_u32 v25, 0, v46, v23
	s_waitcnt lgkmcnt(1)
	v_mfma_f32_16x16x32_bf16 v[0:3], v[42:45], v[34:37], v[0:3]
	ds_read_b128 v[34:37], v25 offset:44032
	v_mad_u32_u24 v25, v16, s85, v198
	v_add3_u32 v27, 0, v49, v25
	ds_read_b128 v[38:41], v27 offset:44032
	ds_read_b128 v[42:45], v22 offset:34880
	v_mad_u32_u24 v22, v16, s85, v199
	v_add3_u32 v27, 0, v52, v22
	s_waitcnt lgkmcnt(2)
	v_mfma_f32_16x16x32_bf16 v[4:7], v[18:21], v[34:37], v[4:7]
	ds_read_b128 v[34:37], v27 offset:44032
	v_mad_u32_u24 v27, v16, s85, v200
	v_add3_u32 v28, 0, v28, v27
	s_waitcnt lgkmcnt(2)
	v_mfma_f32_16x16x32_bf16 v[8:11], v[18:21], v[38:41], v[8:11]
	ds_read_b128 v[38:41], v28 offset:44032
	s_waitcnt lgkmcnt(1)
	v_mfma_f32_16x16x32_bf16 v[34:37], v[18:21], v[34:37], v[12:15]
	s_nop 2
	v_add3_u32 v12, 0, v55, v23
	ds_read_b128 v[12:15], v12 offset:44032
	s_waitcnt lgkmcnt(1)
	v_mfma_f32_16x16x32_bf16 v[0:3], v[18:21], v[38:41], v[0:3]
	v_add3_u32 v18, 0, v56, v25
	ds_read_b128 v[18:21], v18 offset:44032
	s_waitcnt lgkmcnt(1)
	v_mfma_f32_16x16x32_bf16 v[12:15], v[42:45], v[12:15], v[4:7]
	s_nop 2
	v_add3_u32 v4, 0, v57, v22
	ds_read_b128 v[4:7], v4 offset:44032
	s_waitcnt lgkmcnt(1)
	v_mfma_f32_16x16x32_bf16 v[8:11], v[42:45], v[18:21], v[8:11]
	v_add3_u32 v18, 0, v58, v27
	ds_read_b128 v[18:21], v18 offset:44032
	s_waitcnt lgkmcnt(0)
	v_mfma_f32_16x16x32_bf16 v[0:3], v[42:45], v[18:21], v[0:3]
	s_nop 3
	v_mul_f32_e64 v18, v10, v10
	v_mul_f32_e64 v19, v11, v11
	v_pk_mul_f32 v[20:21], v[8:9], v[8:9]
	v_mfma_f32_16x16x32_bf16 v[4:7], v[42:45], v[4:7], v[34:37]
	v_mul_f32_e64 v22, v2, v2
	v_mul_f32_e64 v23, v3, v3
	v_pk_mul_f32 v[28:29], v[0:1], v[0:1]
	v_pk_fma_f32 v[18:19], v[14:15], v[14:15], v[18:19]
	v_pk_fma_f32 v[20:21], v[12:13], v[12:13], v[20:21]
	s_nop 2
	v_pk_fma_f32 v[22:23], v[6:7], v[6:7], v[22:23]
	v_pk_fma_f32 v[28:29], v[4:5], v[4:5], v[28:29]
	v_pk_add_f32 v[22:23], v[18:19], v[22:23]
	v_pk_add_f32 v[18:19], v[20:21], v[28:29]
	s_nop 0
	v_mov_b32_dpp v28, v22 quad_perm:[1,0,3,2] row_mask:0xf bank_mask:0xf bound_ctrl:1
	v_mov_b32_dpp v20, v18 quad_perm:[1,0,3,2] row_mask:0xf bank_mask:0xf bound_ctrl:1
	v_mov_b32_dpp v21, v19 quad_perm:[1,0,3,2] row_mask:0xf bank_mask:0xf bound_ctrl:1
	v_mov_b32_dpp v29, v23 quad_perm:[1,0,3,2] row_mask:0xf bank_mask:0xf bound_ctrl:1
	v_pk_add_f32 v[18:19], v[18:19], v[20:21]
	v_pk_add_f32 v[22:23], v[22:23], v[28:29]
	s_nop 0
	v_mov_b32_dpp v20, v18 quad_perm:[2,3,0,1] row_mask:0xf bank_mask:0xf bound_ctrl:1
	v_mov_b32_dpp v21, v19 quad_perm:[2,3,0,1] row_mask:0xf bank_mask:0xf bound_ctrl:1
	v_mov_b32_dpp v28, v22 quad_perm:[2,3,0,1] row_mask:0xf bank_mask:0xf bound_ctrl:1
	v_mov_b32_dpp v29, v23 quad_perm:[2,3,0,1] row_mask:0xf bank_mask:0xf bound_ctrl:1
	v_pk_add_f32 v[18:19], v[18:19], v[20:21]
	v_pk_add_f32 v[22:23], v[22:23], v[28:29]
	s_nop 0
	v_mov_b32_dpp v20, v18 row_half_mirror row_mask:0xf bank_mask:0xf bound_ctrl:1
	v_mov_b32_dpp v21, v19 row_half_mirror row_mask:0xf bank_mask:0xf bound_ctrl:1
	v_mov_b32_dpp v28, v22 row_half_mirror row_mask:0xf bank_mask:0xf bound_ctrl:1
	v_mov_b32_dpp v29, v23 row_half_mirror row_mask:0xf bank_mask:0xf bound_ctrl:1
	v_pk_add_f32 v[18:19], v[18:19], v[20:21]
	v_pk_add_f32 v[22:23], v[22:23], v[28:29]
	s_nop 0
	v_mov_b32_dpp v20, v18 row_mirror row_mask:0xf bank_mask:0xf bound_ctrl:1
	v_mov_b32_dpp v21, v19 row_mirror row_mask:0xf bank_mask:0xf bound_ctrl:1
	v_mov_b32_dpp v28, v22 row_mirror row_mask:0xf bank_mask:0xf bound_ctrl:1
	v_mov_b32_dpp v29, v23 row_mirror row_mask:0xf bank_mask:0xf bound_ctrl:1
	s_and_saveexec_b64 s[16:17], vcc
	s_cbranch_execz .LBB0_1031
	s_lshl_b32 s19, s19, 2
	s_add_i32 s19, s19, 0
	s_lshl_b32 s18, s18, 2
	s_add_i32 s19, s19, s18
	v_add_u32_e32 v17, s19, v17
	v_add_u32_e32 v17, 0x1fe00, v17
	v_pk_add_f32 v[18:19], v[18:19], v[20:21]
	v_pk_add_f32 v[20:21], v[22:23], v[28:29]
	ds_write_b128 v17, v[18:21]
	s_branch .LBB0_1031
